# stack8 + mLSTM-out gate scan with DPP row shifts/broadcasts instead of 13 ds_bpermute round trips
# speedup vs baseline: 1.0200x; 1.0075x over previous
; #define LAS __attribute__((address_space(3)))
; __device__ __forceinline__ float lx_up(float v, int o, int lane) { return __int_as_float(__builtin_amdgcn_ds_bpermute((lane - o) << 2, __float_as_int(v))); }
; __device__ __forceinline__ float lx_get(float v, int src) { return __int_as_float(__builtin_amdgcn_readlane(__float_as_int(v), src)); }
; __device__ __forceinline__ float wave_incl_sum(float v, int lane) {
; #pragma unroll
;     for (int o = 1; o < 64; o <<= 1) { const float t = lx_up(v, o, lane); if (lane >= o) v += t; }
;     return v;
; }
; __device__ __forceinline__ float wave_incl_max(float v, int lane) {
; #pragma unroll
;     for (int o = 1; o < 64; o <<= 1) { const float t = lx_up(v, o, lane); if (lane >= o) v = fmaxf(v, t); }
;     return v;
; }
; __device__ __forceinline__ void gate_compute(const GateRaw& r, int dir, float m0, LAS float* bL, LAS float* gL, LAS float* ML, int lane, float& Gmax, float& bend) {
;     const int p0 = 2 * lane, t0 = dir ? 127 - p0 : p0, t1 = dir ? t0 - 1 : t0 + 1;
;     const float incl = wave_incl_sum(r.lf0 + r.lf1, lane), excl = incl - (r.lf0 + r.lf1);
;     const float b0 = excl + r.lf0, b1 = incl, g0 = r.li0 - b0, g1 = r.li1 - b1;
;     const float gi = wave_incl_max(fmaxf(g0, g1), lane); float ge = lx_up(gi, 1, lane); if (lane == 0) ge = -INFINITY;
;     const float G0 = fmaxf(ge, g0), G1 = gi;
;     bL[t0] = b0; bL[t1] = b1; gL[t0] = g0; gL[t1] = g1; ML[t0] = fmaxf(m0, G0); ML[t1] = fmaxf(m0, G1);
;     Gmax = lx_get(gi, 63); bend = lx_get(incl, 63);
; }
.LBB0_433:
	v_add_f32_e32 v2, v162, v143
	v_max_f32_e32 v9, v217, v217
	v_mov_b32_e32 v4, v2
	s_nop 1
	v_add_f32_dpp v4, v4, v4 row_shr:1 row_mask:0xf bank_mask:0xf
	s_nop 1
	v_add_f32_dpp v4, v4, v4 row_shr:2 row_mask:0xf bank_mask:0xf
	s_nop 1
	v_add_f32_dpp v4, v4, v4 row_shr:4 row_mask:0xf bank_mask:0xf
	s_nop 1
	v_add_f32_dpp v4, v4, v4 row_shr:8 row_mask:0xf bank_mask:0xf
	s_nop 1
	v_add_f32_dpp v4, v4, v4 row_bcast:15 row_mask:0xa bank_mask:0xf
	s_nop 1
	v_add_f32_dpp v4, v4, v4 row_bcast:31 row_mask:0xc bank_mask:0xf
	v_sub_f32_e32 v2, v4, v2
	v_add_f32_e32 v2, v143, v2
	v_sub_f32_e32 v5, v163, v4
	v_sub_f32_e32 v6, v137, v2
	v_max_f32_e32 v7, v6, v5
	ds_write_b32 v172, v2 offset:32768
	ds_write_b32 v172, v6 offset:33280
	ds_write2st64_b32 v173, v4, v5 offset0:128 offset1:130
	s_nop 1
	v_max_f32_dpp v7, v7, v7 row_shr:1 row_mask:0xf bank_mask:0xf
	s_nop 1
	v_max_f32_dpp v7, v7, v7 row_shr:2 row_mask:0xf bank_mask:0xf
	s_nop 1
	v_max_f32_dpp v7, v7, v7 row_shr:4 row_mask:0xf bank_mask:0xf
	s_nop 1
	v_max_f32_dpp v7, v7, v7 row_shr:8 row_mask:0xf bank_mask:0xf
	s_nop 1
	v_max_f32_dpp v7, v7, v7 row_bcast:15 row_mask:0xa bank_mask:0xf
	s_nop 1
	v_max_f32_dpp v7, v7, v7 row_bcast:31 row_mask:0xc bank_mask:0xf
	v_mov_b32_e32 v8, v243
	s_nop 1
	v_mov_b32_dpp v8, v7 wave_shr:1 row_mask:0xf bank_mask:0xf
	v_max_f32_e32 v2, v9, v7
	s_nop 0
	v_max3_f32 v4, v217, v8, v6
	ds_write_b32 v172, v4 offset:33792
	ds_write_b32 v173, v2 offset:33792
	ds_write_b32 v174, v216 offset:36864
	s_and_saveexec_b64 s[0:1], s[42:43]
	s_add_i32 s6, s83, s84
	v_mov_b32_e32 v2, s6
	ds_write_b32 v2, v217 offset:37376
	s_or_b64 exec, exec, s[0:1]
	s_and_saveexec_b64 s[0:1], s[38:39]
	s_cbranch_execnz .LBB0_416
	s_branch .LBB0_417
